# stack3 plus: XCD leader releases its local workgroups without first waiting for the TOPGEN atomic's ack
# speedup vs baseline: 1.0195x; 1.0067x over previous
.LBB0_111:
	s_or_b64 exec, exec, s[6:7]
	s_mov_b64 s[6:7], exec
	v_mbcnt_lo_u32_b32 v1, s6, 0
	v_mbcnt_hi_u32_b32 v1, s7, v1
	v_cmp_eq_u32_e32 vcc, 0, v1
	s_and_saveexec_b64 s[10:11], vcc
	s_cbranch_execz .LBB0_113
	s_bcnt1_i32_b64 s6, s[6:7]
	v_mov_b32_e32 v1, 0
	v_mov_b32_e32 v2, s6
	global_atomic_add v1, v2, s[8:9]

.LBB0_2283:
	s_or_b64 exec, exec, s[4:5]
	s_mov_b64 s[4:5], exec
	v_mbcnt_lo_u32_b32 v1, s4, 0
	v_mbcnt_hi_u32_b32 v1, s5, v1
	v_cmp_eq_u32_e32 vcc, 0, v1
	s_and_saveexec_b64 s[8:9], vcc
	s_cbranch_execz .LBB0_2285
	s_bcnt1_i32_b64 s4, s[4:5]
	v_mov_b32_e32 v1, 0
	v_mov_b32_e32 v2, s4
	global_atomic_add v1, v2, s[6:7]

.LBB0_3455:
	s_or_b64 exec, exec, s[4:5]
	s_mov_b64 s[4:5], exec
	v_mbcnt_lo_u32_b32 v1, s4, 0
	v_mbcnt_hi_u32_b32 v1, s5, v1
	v_cmp_eq_u32_e32 vcc, 0, v1
	s_and_saveexec_b64 s[8:9], vcc
	s_cbranch_execz .LBB0_3457
	s_bcnt1_i32_b64 s3, s[4:5]
	v_mov_b32_e32 v1, 0
	v_mov_b32_e32 v2, s3
	global_atomic_add v1, v2, s[6:7]

.LBB0_3553:
	s_or_b64 exec, exec, s[2:3]
	s_mov_b64 s[2:3], exec
	v_mbcnt_lo_u32_b32 v1, s2, 0
	v_mbcnt_hi_u32_b32 v1, s3, v1
	v_cmp_eq_u32_e32 vcc, 0, v1
	s_and_saveexec_b64 s[6:7], vcc
	s_cbranch_execz .LBB0_3555
	s_bcnt1_i32_b64 s2, s[2:3]
	v_mov_b32_e32 v1, 0
	v_mov_b32_e32 v2, s2
	global_atomic_add v1, v2, s[4:5]

.LBB0_3623:
	s_or_b64 exec, exec, s[2:3]
	s_mov_b64 s[2:3], exec
	v_mbcnt_lo_u32_b32 v0, s2, 0
	v_mbcnt_hi_u32_b32 v0, s3, v0
	v_cmp_eq_u32_e32 vcc, 0, v0
	s_and_saveexec_b64 s[6:7], vcc
	s_cbranch_execz .LBB0_3625
	s_bcnt1_i32_b64 s2, s[2:3]
	v_mov_b32_e32 v0, 0
	v_mov_b32_e32 v1, s2
	global_atomic_add v0, v1, s[4:5]
